# S5: pipelined chunk loop (B-proj of next chunk inside scan, plain-fma scan, u/usk prefetch via parity register sets); attention: dropped needless vmcnt drain before QK
# speedup vs baseline: 1.0054x; 1.0054x over previous
.LBB0_302:
	s_or_b64 exec, exec, s[54:55]
	v_cndmask_b32_e64 v0, v151, v119, s[4:5]
	v_mov_b32_e32 v126, 0xffffa000
	v_lshlrev_b32_e32 v119, 8, v151
	v_lshl_add_u32 v0, v0, 10, v126
	v_cndmask_b32_e64 v0, v119, v0, s[4:5]
	v_or_b32_e32 v128, v0, v133
	v_ashrrev_i32_e32 v129, 31, v128
	v_lshlrev_b32_e32 v139, 4, v121
	v_lshlrev_b64 v[126:127], 12, v[128:129]
	v_lshl_add_u64 v[126:127], s[12:13], 0, v[126:127]
	v_lshlrev_b32_e32 v0, 2, v139
	v_lshl_add_u64 v[130:131], v[126:127], 0, v[0:1]
	v_mov_b32_e32 v119, v1
	v_lshl_add_u64 v[126:127], v[130:131], 0, v[118:119]
	v_mov_b32_e32 v0, 0xc648000
	v_mov_b32_e32 v119, 0x9e48000
	v_cndmask_b32_e32 v0, v0, v119, vcc
	v_lshl_add_u64 v[166:167], s[28:29], 0, v[0:1]
	v_lshlrev_b64 v[128:129], 11, v[128:129]
	v_lshl_add_u64 v[128:129], v[166:167], 0, v[128:129]
	s_waitcnt vmcnt(25)
	v_pk_mul_f32 v[166:167], v[142:143], v[98:99] op_sel:[1,0]
	v_pk_mul_f32 v[98:99], v[142:143], v[98:99] op_sel_hi:[0,1]
	v_pk_fma_f32 v[166:167], v[142:143], v[94:95], v[166:167] op_sel_hi:[0,1,1] neg_lo:[0,0,1] neg_hi:[0,0,1]
	v_pk_fma_f32 v[94:95], v[142:143], v[94:95], v[98:99] op_sel:[1,0,0]
	v_pk_mul_f32 v[98:99], v[142:143], v[100:101] op_sel:[1,0]
	v_pk_mul_f32 v[100:101], v[142:143], v[100:101] op_sel_hi:[0,1]
	v_pk_fma_f32 v[98:99], v[142:143], v[96:97], v[98:99] op_sel_hi:[0,1,1] neg_lo:[0,0,1] neg_hi:[0,0,1]
	v_pk_fma_f32 v[96:97], v[142:143], v[96:97], v[100:101] op_sel:[1,0,0]
	v_pk_mul_f32 v[100:101], v[142:143], v[10:11] op_sel:[1,0]
	v_pk_mul_f32 v[10:11], v[142:143], v[10:11] op_sel_hi:[0,1]
	v_pk_fma_f32 v[168:169], v[142:143], v[6:7], v[10:11] op_sel:[1,0,0]
	v_cvt_pk_bf16_f32 v10, v94, v95
	s_waitcnt vmcnt(20)
	v_pk_mul_f32 v[94:95], v[140:141], v[90:91] op_sel:[1,0]
	v_pk_mul_f32 v[90:91], v[140:141], v[90:91] op_sel_hi:[0,1]
	v_pk_fma_f32 v[94:95], v[140:141], v[86:87], v[94:95] op_sel_hi:[0,1,1] neg_lo:[0,0,1] neg_hi:[0,0,1]
	v_pk_fma_f32 v[86:87], v[140:141], v[86:87], v[90:91] op_sel:[1,0,0]
	v_pk_mul_f32 v[90:91], v[140:141], v[92:93] op_sel:[1,0]
	v_pk_mul_f32 v[92:93], v[140:141], v[92:93] op_sel_hi:[0,1]
	v_pk_fma_f32 v[90:91], v[140:141], v[88:89], v[90:91] op_sel_hi:[0,1,1] neg_lo:[0,0,1] neg_hi:[0,0,1]
	v_pk_fma_f32 v[88:89], v[140:141], v[88:89], v[92:93] op_sel:[1,0,0]
	v_pk_mul_f32 v[92:93], v[140:141], v[18:19] op_sel:[1,0]
	v_pk_mul_f32 v[18:19], v[140:141], v[18:19] op_sel_hi:[0,1]
	v_lshlrev_b32_e32 v0, 1, v139
	v_cvt_pk_bf16_f32 v11, v96, v97
	v_pk_fma_f32 v[96:97], v[140:141], v[14:15], v[18:19] op_sel:[1,0,0]
	v_cvt_pk_bf16_f32 v18, v86, v87
	s_waitcnt vmcnt(15)
	v_pk_mul_f32 v[86:87], v[136:137], v[82:83] op_sel:[1,0]
	v_pk_mul_f32 v[82:83], v[136:137], v[82:83] op_sel_hi:[0,1]
	v_lshl_add_u64 v[128:129], v[128:129], 0, v[0:1]
	v_lshlrev_b32_e32 v0, 1, v106
	v_pk_fma_f32 v[86:87], v[136:137], v[78:79], v[86:87] op_sel_hi:[0,1,1] neg_lo:[0,0,1] neg_hi:[0,0,1]
	v_pk_fma_f32 v[78:79], v[136:137], v[78:79], v[82:83] op_sel:[1,0,0]
	v_pk_mul_f32 v[82:83], v[136:137], v[84:85] op_sel:[1,0]
	v_pk_mul_f32 v[84:85], v[136:137], v[84:85] op_sel_hi:[0,1]
	v_lshl_add_u64 v[128:129], v[128:129], 0, v[0:1]
	v_lshlrev_b32_e32 v0, 2, v106
	v_pk_fma_f32 v[82:83], v[136:137], v[80:81], v[82:83] op_sel_hi:[0,1,1] neg_lo:[0,0,1] neg_hi:[0,0,1]
	v_pk_fma_f32 v[80:81], v[136:137], v[80:81], v[84:85] op_sel:[1,0,0]
	v_pk_mul_f32 v[84:85], v[136:137], v[26:27] op_sel:[1,0]
	v_pk_mul_f32 v[26:27], v[136:137], v[26:27] op_sel_hi:[0,1]
	v_lshl_add_u64 v[130:131], v[130:131], 0, v[0:1]
	v_pk_fma_f32 v[100:101], v[142:143], v[6:7], v[100:101] op_sel_hi:[0,1,1] neg_lo:[0,0,1] neg_hi:[0,0,1]
	v_pk_mul_f32 v[6:7], v[142:143], v[12:13] op_sel:[1,0]
	v_cvt_pk_bf16_f32 v19, v88, v89
	v_pk_fma_f32 v[88:89], v[136:137], v[22:23], v[26:27] op_sel:[1,0,0]
	v_cvt_pk_bf16_f32 v26, v78, v79
	s_waitcnt vmcnt(10)
	v_pk_mul_f32 v[78:79], v[134:135], v[74:75] op_sel:[1,0]
	v_pk_mul_f32 v[74:75], v[134:135], v[74:75] op_sel_hi:[0,1]
	s_waitcnt vmcnt(7)
	v_xor_b32_e32 v0, 0x80000000, v66
	v_pk_fma_f32 v[170:171], v[142:143], v[8:9], v[6:7] op_sel_hi:[0,1,1] neg_lo:[0,0,1] neg_hi:[0,0,1]
	v_pk_mul_f32 v[6:7], v[142:143], v[12:13] op_sel_hi:[0,1]
	v_pk_fma_f32 v[92:93], v[140:141], v[14:15], v[92:93] op_sel_hi:[0,1,1] neg_lo:[0,0,1] neg_hi:[0,0,1]
	v_pk_mul_f32 v[14:15], v[140:141], v[20:21] op_sel:[1,0]
	v_pk_fma_f32 v[78:79], v[134:135], v[70:71], v[78:79] op_sel_hi:[0,1,1] neg_lo:[0,0,1] neg_hi:[0,0,1]
	v_pk_fma_f32 v[70:71], v[134:135], v[70:71], v[74:75] op_sel:[1,0,0]
	v_pk_mul_f32 v[74:75], v[134:135], v[76:77] op_sel:[1,0]
	v_pk_mul_f32 v[76:77], v[134:135], v[76:77] op_sel_hi:[0,1]
	v_cvt_pk_bf16_f32 v38, v38, v0
	s_waitcnt vmcnt(6)
	v_xor_b32_e32 v0, 0x80000000, v62
	v_pk_fma_f32 v[142:143], v[142:143], v[8:9], v[6:7] op_sel:[1,0,0]
	v_cvt_pk_bf16_f32 v7, v98, v99
	v_pk_fma_f32 v[98:99], v[140:141], v[16:17], v[14:15] op_sel_hi:[0,1,1] neg_lo:[0,0,1] neg_hi:[0,0,1]
	v_pk_mul_f32 v[14:15], v[140:141], v[20:21] op_sel_hi:[0,1]
	v_pk_fma_f32 v[84:85], v[136:137], v[22:23], v[84:85] op_sel_hi:[0,1,1] neg_lo:[0,0,1] neg_hi:[0,0,1]
	v_pk_mul_f32 v[22:23], v[136:137], v[28:29] op_sel:[1,0]
	v_pk_fma_f32 v[74:75], v[134:135], v[72:73], v[74:75] op_sel_hi:[0,1,1] neg_lo:[0,0,1] neg_hi:[0,0,1]
	v_pk_fma_f32 v[72:73], v[134:135], v[72:73], v[76:77] op_sel:[1,0,0]
	v_pk_mul_f32 v[76:77], v[134:135], v[34:35] op_sel:[1,0]
	v_pk_mul_f32 v[34:35], v[134:135], v[34:35] op_sel_hi:[0,1]
	v_cvt_pk_bf16_f32 v42, v42, v0
	s_waitcnt vmcnt(3)
	v_xor_b32_e32 v0, 0x80000000, v58
	v_cvt_pk_bf16_f32 v8, v100, v101
	v_pk_fma_f32 v[100:101], v[140:141], v[16:17], v[14:15] op_sel:[1,0,0]
	v_cvt_pk_bf16_f32 v15, v90, v91
	v_pk_fma_f32 v[90:91], v[136:137], v[24:25], v[22:23] op_sel_hi:[0,1,1] neg_lo:[0,0,1] neg_hi:[0,0,1]
	v_pk_mul_f32 v[22:23], v[136:137], v[28:29] op_sel_hi:[0,1]
	v_cvt_pk_bf16_f32 v27, v80, v81
	v_pk_fma_f32 v[76:77], v[134:135], v[30:31], v[76:77] op_sel_hi:[0,1,1] neg_lo:[0,0,1] neg_hi:[0,0,1]
	v_pk_fma_f32 v[80:81], v[134:135], v[30:31], v[34:35] op_sel:[1,0,0]
	v_pk_mul_f32 v[30:31], v[134:135], v[36:37] op_sel:[1,0]
	v_cvt_pk_bf16_f32 v46, v46, v0
	s_waitcnt vmcnt(2)
	v_xor_b32_e32 v0, 0x80000000, v54
	v_xor_b32_e32 v54, 0x80000000, v55
	v_mov_b32_e32 v139, v1
	v_cvt_pk_bf16_f32 v16, v92, v93
	v_pk_fma_f32 v[92:93], v[136:137], v[24:25], v[22:23] op_sel:[1,0,0]
	v_cvt_pk_bf16_f32 v23, v82, v83
	v_pk_fma_f32 v[82:83], v[134:135], v[32:33], v[30:31] op_sel_hi:[0,1,1] neg_lo:[0,0,1] neg_hi:[0,0,1]
	v_pk_mul_f32 v[30:31], v[134:135], v[36:37] op_sel_hi:[0,1]
	v_cvt_pk_bf16_f32 v51, v51, v54
	v_lshlrev_b64 v[54:55], 12, v[138:139]
	v_cvt_pk_bf16_f32 v24, v84, v85
	v_pk_fma_f32 v[84:85], v[134:135], v[32:33], v[30:31] op_sel:[1,0,0]
	v_lshl_add_u64 v[54:55], v[126:127], 0, v[54:55]
	v_cvt_pk_bf16_f32 v22, v86, v87
	v_cvt_pk_bf16_f32 v28, v88, v89
	v_cvt_pk_bf16_f32 v33, v82, v83
	v_cvt_pk_bf16_f32 v37, v84, v85
	global_load_dwordx4 v[82:85], v[54:55], off offset:16
	global_load_dwordx4 v[86:89], v[54:55], off
	v_add_u32_e32 v54, v165, v138
	v_ashrrev_i32_e32 v55, 31, v54
	v_cvt_pk_bf16_f32 v34, v70, v71
	v_xor_b32_e32 v70, 0x80000000, v56
	v_xor_b32_e32 v71, 0x80000000, v57
	v_lshlrev_b64 v[56:57], 12, v[54:55]
	v_add_u32_e32 v54, v54, v165
	v_ashrrev_i32_e32 v55, 31, v54
	v_xor_b32_e32 v66, 0x80000000, v67
	v_xor_b32_e32 v67, 0x80000000, v68
	v_xor_b32_e32 v58, 0x80000000, v59
	v_xor_b32_e32 v59, 0x80000000, v60
	v_lshlrev_b64 v[54:55], 12, v[54:55]
	v_xor_b32_e32 v68, 0x80000000, v69
	v_cvt_pk_bf16_f32 v39, v39, v66
	v_cvt_pk_bf16_f32 v40, v40, v67
	v_xor_b32_e32 v62, 0x80000000, v63
	v_xor_b32_e32 v63, 0x80000000, v64
	v_xor_b32_e32 v64, 0x80000000, v65
	v_xor_b32_e32 v60, 0x80000000, v61
	v_cvt_pk_bf16_f32 v47, v47, v58
	v_cvt_pk_bf16_f32 v48, v48, v59
	v_lshl_add_u64 v[66:67], v[126:127], 0, v[56:57]
	v_lshl_add_u64 v[58:59], v[126:127], 0, v[54:55]
	v_cvt_pk_bf16_f32 v41, v41, v68
	v_cvt_pk_bf16_f32 v43, v43, v62
	v_cvt_pk_bf16_f32 v44, v44, v63
	v_cvt_pk_bf16_f32 v45, v45, v64
	v_cvt_pk_bf16_f32 v49, v49, v60
	global_load_dwordx4 v[54:57], v[58:59], off offset:16
	s_nop 0
	global_load_dwordx4 v[58:61], v[58:59], off
	s_nop 0
	global_load_dwordx4 v[62:65], v[66:67], off offset:16
	s_nop 0
	global_load_dwordx4 v[66:69], v[66:67], off
	v_cvt_pk_bf16_f32 v52, v52, v70
	v_mul_u32_u24_e32 v70, 0x84, v125
	v_cvt_pk_bf16_f32 v17, v98, v99
	v_lshl_add_u32 v98, v70, 2, v147
	v_mul_u32_u24_e32 v70, 0x84, v154
	v_lshl_add_u32 v99, v70, 2, v147
	v_mul_u32_u24_e32 v70, 0x84, v155
	v_cvt_pk_bf16_f32 v21, v100, v101
	v_lshl_add_u32 v100, v70, 2, v147
	v_mul_u32_u24_e32 v70, 0x84, v157
	v_lshl_add_u32 v101, v70, 2, v147
	v_mul_u32_u24_e32 v70, 0x84, v152
	v_lshl_add_u32 v119, v70, 2, v147
	v_mul_u32_u24_e32 v70, 0x84, v159
	v_lshl_add_u32 v134, v70, 2, v147
	v_mul_u32_u24_e32 v70, 0x84, v153
	v_lshl_add_u32 v135, v70, 2, v147
	v_add_u32_e32 v70, 7, v150
	v_cvt_pk_bf16_f32 v53, v53, v71
	v_mul_u32_u24_e32 v71, 0x84, v70
	v_lshl_add_u32 v136, v71, 2, v147
	v_sub_u32_e32 v71, 8, v150
	v_cvt_pk_bf16_f32 v35, v72, v73
	v_mul_u32_u24_e32 v72, 0x84, v71
	v_lshl_add_u32 v137, v72, 2, v147
	v_mul_u32_u24_e32 v72, 0x84, v156
	v_lshl_add_u32 v138, v72, 2, v147
	v_mul_u32_u24_e32 v72, 0x84, v158
	v_lshl_add_u32 v139, v72, 2, v147
	v_mul_u32_u24_e32 v72, 0x84, v160
	v_lshl_add_u32 v140, v72, 2, v147
	v_mul_u32_u24_e32 v72, 0x84, v161
	v_lshl_add_u32 v141, v72, 2, v147
	v_mul_u32_u24_e32 v72, 0x84, v162
	v_cvt_pk_bf16_f32 v13, v142, v143
	v_lshl_add_u32 v142, v72, 2, v147
	v_mul_u32_u24_e32 v72, 0x84, v163
	v_lshl_add_u32 v143, v72, 2, v147
	v_mul_u32_u24_e32 v72, 0x84, v164
	v_cvt_pk_bf16_f32 v31, v74, v75
	v_cvt_pk_bf16_f32 v32, v76, v77
	v_cvt_pk_bf16_f32 v50, v50, v0
	v_mul_i32_i24_e32 v0, 3, v165
	v_lshl_add_u32 v165, v72, 2, v147
	v_mul_u32_u24_e32 v72, 0x110, v125
	v_mul_u32_u24_e32 v73, 0x110, v154
	v_mul_u32_u24_e32 v74, 0x110, v155
	v_mul_u32_u24_e32 v75, 0x110, v157
	v_mul_u32_u24_e32 v76, 0x110, v152
	v_mul_u32_u24_e32 v77, 0x110, v159
	v_mul_u32_u24_e32 v70, 0x110, v70
	v_mul_u32_u24_e32 v71, 0x110, v71
	v_cvt_pk_bf16_f32 v12, v168, v169
	v_cvt_pk_bf16_f32 v20, v96, v97
	v_cvt_pk_bf16_f32 v30, v78, v79
	v_cvt_pk_bf16_f32 v36, v80, v81
	v_mul_u32_u24_e32 v78, 0x110, v153
	v_mul_u32_u24_e32 v79, 0x110, v156
	v_mul_u32_u24_e32 v80, 0x110, v158
	v_mul_u32_u24_e32 v81, 0x110, v160
	v_mul_u32_u24_e32 v96, 0x110, v161
	v_mul_u32_u24_e32 v97, 0x110, v162
	v_mul_u32_u24_e32 v125, 0x110, v163
	v_mul_u32_u24_e32 v168, 0x110, v164
	v_add_u32_e32 v152, v147, v72
	v_add_u32_e32 v153, v147, v73
	v_add_u32_e32 v154, v147, v74
	v_add_u32_e32 v155, v147, v75
	v_add_u32_e32 v156, v147, v76
	v_add_u32_e32 v157, v147, v77
	v_add_u32_e32 v159, v147, v70
	v_add_u32_e32 v160, v147, v71
	s_mov_b32 s22, 0
	v_cvt_pk_bf16_f32 v6, v166, v167
	v_cvt_pk_bf16_f32 v9, v170, v171
	v_cvt_pk_bf16_f32 v14, v94, v95
	s_waitcnt vmcnt(3)
	v_mov_b64_e32 v[72:73], v[56:57]
	s_waitcnt vmcnt(2)
	v_mov_b64_e32 v[76:77], v[60:61]
	v_cvt_pk_bf16_f32 v25, v90, v91
	v_cvt_pk_bf16_f32 v29, v92, v93
	v_mov_b32_e32 v90, 0
	v_cndmask_b32_e32 v90, v146, v90, vcc
	v_ashrrev_i32_e32 v91, 31, v90
	v_lshlrev_b64 v[90:91], 12, v[90:91]
	v_lshl_add_u64 v[90:91], v[130:131], 0, v[90:91]
	global_load_dwordx4 v[90:93], v[90:91], off


	s_mov_b64 s[54:55], 0
	v_add_u32_e32 v158, v147, v78
	v_add_u32_e32 v161, v147, v79
	v_add_u32_e32 v162, v147, v80
	v_add_u32_e32 v163, v147, v81
	v_add_u32_e32 v164, v147, v96
	v_add_u32_e32 v166, v147, v97
	v_add_u32_e32 v167, v147, v125
	v_add_u32_e32 v168, v147, v168
	v_mov_b32_e32 v169, v146
	s_mov_b32 s23, 0
	v_mov_b64_e32 v[70:71], v[54:55]
	v_mov_b64_e32 v[74:75], v[58:59]
	s_waitcnt vmcnt(0)
	v_cvt_pk_bf16_f32 v125, v86, v87
	v_lshlrev_b32_e32 v170, 16, v125
	v_and_b32_e32 v171, 0xffff0000, v125
	v_cvt_pk_bf16_f32 v172, v88, v89
	v_pk_add_f32 v[86:87], v[86:87], v[170:171] neg_lo:[0,1] neg_hi:[0,1]
	v_cvt_pk_bf16_f32 v173, v82, v83
	v_cvt_pk_bf16_f32 v170, v86, v87
	v_lshlrev_b32_e32 v86, 16, v172
	v_and_b32_e32 v87, 0xffff0000, v172
	v_pk_add_f32 v[86:87], v[88:89], v[86:87] neg_lo:[0,1] neg_hi:[0,1]
	v_cvt_pk_bf16_f32 v178, v84, v85
	v_cvt_pk_bf16_f32 v88, v86, v87
	v_lshlrev_b32_e32 v86, 16, v173
	v_and_b32_e32 v87, 0xffff0000, v173
	v_pk_add_f32 v[82:83], v[82:83], v[86:87] neg_lo:[0,1] neg_hi:[0,1]
	v_cvt_pk_bf16_f32 v86, v82, v83
	v_lshlrev_b32_e32 v82, 16, v178
	v_and_b32_e32 v83, 0xffff0000, v178
	v_pk_add_f32 v[82:83], v[84:85], v[82:83] neg_lo:[0,1] neg_hi:[0,1]
	v_cndmask_b32_e64 v84, v86, v173, s[6:7]
	v_cvt_pk_bf16_f32 v82, v82, v83
	v_cndmask_b32_e64 v85, v82, v178, s[6:7]
	v_cndmask_b32_e64 v83, v88, v172, s[6:7]
	v_cndmask_b32_e64 v82, v170, v125, s[6:7]
	s_nop 1
	v_mfma_f32_16x16x32_bf16 v[86:89], v[6:9], v[82:85], 0
	v_mfma_f32_16x16x32_bf16 v[170:173], v[14:17], v[82:85], 0
	v_mfma_f32_16x16x32_bf16 v[178:181], v[22:25], v[82:85], 0
	v_mfma_f32_16x16x32_bf16 v[182:185], v[30:33], v[82:85], 0
	v_mfma_f32_16x16x32_bf16 v[186:189], v[10:13], v[82:85], 0
	v_mfma_f32_16x16x32_bf16 v[210:213], v[18:21], v[82:85], 0
	v_mfma_f32_16x16x32_bf16 v[214:217], v[26:29], v[82:85], 0
	v_mfma_f32_16x16x32_bf16 v[82:85], v[34:37], v[82:85], 0
	s_nop 0
	ds_write_b128 v148, v[86:89]
	ds_write_b128 v148, v[170:173] offset:64
	ds_write_b128 v148, v[178:181] offset:128
	ds_write_b128 v148, v[182:185] offset:192
	ds_write_b128 v148, v[186:189] offset:256
	ds_write_b128 v148, v[210:213] offset:320
	ds_write_b128 v148, v[214:217] offset:384
	ds_write_b128 v148, v[82:85] offset:448
	s_branch .LBB0_304
.LBB0_303:
	ds_read2st64_b32 v[82:83], v98 offset1:1
	ds_read2st64_b32 v[84:85], v99 offset1:1
	ds_read2st64_b32 v[86:87], v100 offset1:1
	ds_read2st64_b32 v[88:89], v101 offset1:1
	ds_read2st64_b32 v[170:171], v119 offset1:1
	ds_read2st64_b32 v[172:173], v134 offset1:1
	ds_read2st64_b32 v[178:179], v135 offset1:1
	ds_read2st64_b32 v[180:181], v136 offset1:1
	ds_read2st64_b32 v[182:183], v137 offset1:1
	ds_read2st64_b32 v[184:185], v138 offset1:1
	ds_read2st64_b32 v[186:187], v139 offset1:1
	ds_read2st64_b32 v[188:189], v140 offset1:1
	ds_read2st64_b32 v[190:191], v141 offset1:1
	ds_read2st64_b32 v[202:203], v142 offset1:1
	ds_read2st64_b32 v[204:205], v143 offset1:1
	ds_read2st64_b32 v[210:211], v165 offset1:1
	v_cvt_pk_bf16_f32 v222, v66, v67
	v_cvt_pk_bf16_f32 v223, v68, v69
	v_cvt_pk_bf16_f32 v224, v62, v63
	v_cvt_pk_bf16_f32 v225, v64, v65
	v_lshlrev_b32_e32 v226, 16, v222
	v_and_b32_e32 v227, 0xffff0000, v222
	v_pk_add_f32 v[228:229], v[66:67], v[226:227] neg_lo:[0,1] neg_hi:[0,1]
	v_cvt_pk_bf16_f32 v230, v228, v229
	v_lshlrev_b32_e32 v226, 16, v223
	v_and_b32_e32 v227, 0xffff0000, v223
	v_pk_add_f32 v[228:229], v[68:69], v[226:227] neg_lo:[0,1] neg_hi:[0,1]
	v_cvt_pk_bf16_f32 v231, v228, v229
	v_lshlrev_b32_e32 v226, 16, v224
	v_and_b32_e32 v227, 0xffff0000, v224
	v_pk_add_f32 v[228:229], v[62:63], v[226:227] neg_lo:[0,1] neg_hi:[0,1]
	v_cvt_pk_bf16_f32 v232, v228, v229
	v_lshlrev_b32_e32 v226, 16, v225
	v_and_b32_e32 v227, 0xffff0000, v225
	v_pk_add_f32 v[228:229], v[64:65], v[226:227] neg_lo:[0,1] neg_hi:[0,1]
	v_cvt_pk_bf16_f32 v233, v228, v229
	v_cndmask_b32_e64 v218, v230, v222, s[6:7]
	v_cndmask_b32_e64 v219, v231, v223, s[6:7]
	v_cndmask_b32_e64 v220, v232, v224, s[6:7]
	v_cndmask_b32_e64 v221, v233, v225, s[6:7]
	v_lshlrev_b64 v[96:97], 10, v[96:97]
	s_add_i32 s23, s23, 1
	s_add_i32 s22, s22, 16
	v_cmp_eq_u32_e64 s[0:1], s23, v145
	v_add_u32_e32 v169, -16, v169
	s_waitcnt lgkmcnt(8)
	v_mfma_f32_16x16x32_bf16 v[222:225], v[6:9], v[218:221], 0
	v_fma_f32 v250, -v123, v132, v82
	v_fma_f32 v209, v123, v124, v83
	v_fma_f32 v216, v122, v124, v250
	v_fma_f32 v217, v122, v132, v209
	v_cvt_pk_bf16_f32 v250, v216, v217
	ds_write_b32 v152, v250 offset:8448
	v_mfma_f32_16x16x32_bf16 v[226:229], v[14:17], v[218:221], 0
	v_fma_f32 v250, -v123, v217, v84
	v_fma_f32 v209, v123, v216, v85
	v_fma_f32 v124, v122, v216, v250
	v_fma_f32 v132, v122, v217, v209
	v_cvt_pk_bf16_f32 v250, v124, v132
	ds_write_b32 v153, v250 offset:8448
	v_mfma_f32_16x16x32_bf16 v[230:233], v[22:25], v[218:221], 0
	v_fma_f32 v250, -v123, v132, v86
	v_fma_f32 v209, v123, v124, v87
	v_fma_f32 v216, v122, v124, v250
	v_fma_f32 v217, v122, v132, v209
	v_cvt_pk_bf16_f32 v250, v216, v217
	ds_write_b32 v154, v250 offset:8448
	v_mfma_f32_16x16x32_bf16 v[234:237], v[30:33], v[218:221], 0
	v_fma_f32 v250, -v123, v217, v88
	v_fma_f32 v209, v123, v216, v89
	v_fma_f32 v124, v122, v216, v250
	v_fma_f32 v132, v122, v217, v209
	v_cvt_pk_bf16_f32 v250, v124, v132
	ds_write_b32 v155, v250 offset:8448
	s_or_b64 s[54:55], s[0:1], s[54:55]
	v_mfma_f32_16x16x32_bf16 v[238:241], v[10:13], v[218:221], 0
	v_fma_f32 v250, -v123, v132, v170
	v_fma_f32 v209, v123, v124, v171
	v_fma_f32 v216, v122, v124, v250
	v_fma_f32 v217, v122, v132, v209
	v_cvt_pk_bf16_f32 v250, v216, v217
	ds_write_b32 v156, v250 offset:8448
	v_mfma_f32_16x16x32_bf16 v[242:245], v[18:21], v[218:221], 0
	v_fma_f32 v250, -v123, v217, v172
	v_fma_f32 v209, v123, v216, v173
	v_fma_f32 v124, v122, v216, v250
	v_fma_f32 v132, v122, v217, v209
	v_cvt_pk_bf16_f32 v250, v124, v132
	ds_write_b32 v157, v250 offset:8448
	v_mfma_f32_16x16x32_bf16 v[246:249], v[26:29], v[218:221], 0
	v_fma_f32 v250, -v123, v132, v178
	v_fma_f32 v209, v123, v124, v179
	v_fma_f32 v216, v122, v124, v250
	v_fma_f32 v217, v122, v132, v209
	v_cvt_pk_bf16_f32 v250, v216, v217
	ds_write_b32 v158, v250 offset:8448
	v_mfma_f32_16x16x32_bf16 v[212:215], v[34:37], v[218:221], 0
	v_fma_f32 v250, -v123, v217, v180
	v_fma_f32 v209, v123, v216, v181
	v_fma_f32 v124, v122, v216, v250
	v_fma_f32 v132, v122, v217, v209
	v_cvt_pk_bf16_f32 v250, v124, v132
	ds_write_b32 v159, v250 offset:8448
	s_waitcnt lgkmcnt(8)
	v_fma_f32 v250, -v123, v132, v182
	v_fma_f32 v209, v123, v124, v183
	v_fma_f32 v216, v122, v124, v250
	v_fma_f32 v217, v122, v132, v209
	v_cvt_pk_bf16_f32 v250, v216, v217
	ds_write_b32 v160, v250 offset:8448
	ds_write_b128 v148, v[222:225]
	ds_write_b128 v148, v[226:229] offset:64
	v_fma_f32 v250, -v123, v217, v184
	v_fma_f32 v209, v123, v216, v185
	v_fma_f32 v124, v122, v216, v250
	v_fma_f32 v132, v122, v217, v209
	v_cvt_pk_bf16_f32 v250, v124, v132
	ds_write_b32 v161, v250 offset:8448
	ds_write_b128 v148, v[230:233] offset:128
	ds_write_b128 v148, v[234:237] offset:192
	v_fma_f32 v250, -v123, v132, v186
	v_fma_f32 v209, v123, v124, v187
	v_fma_f32 v216, v122, v124, v250
	v_fma_f32 v217, v122, v132, v209
	v_cvt_pk_bf16_f32 v250, v216, v217
	ds_write_b32 v162, v250 offset:8448
	ds_write_b128 v148, v[238:241] offset:256
	ds_write_b128 v148, v[242:245] offset:320
	v_fma_f32 v250, -v123, v217, v188
	v_fma_f32 v209, v123, v216, v189
	v_fma_f32 v124, v122, v216, v250
	v_fma_f32 v132, v122, v217, v209
	v_cvt_pk_bf16_f32 v250, v124, v132
	ds_write_b32 v163, v250 offset:8448
	ds_write_b128 v148, v[246:249] offset:384
	ds_write_b128 v148, v[212:215] offset:448
	v_fma_f32 v250, -v123, v132, v190
	v_fma_f32 v209, v123, v124, v191
	v_fma_f32 v216, v122, v124, v250
	v_fma_f32 v217, v122, v132, v209
	v_cvt_pk_bf16_f32 v250, v216, v217
	ds_write_b32 v164, v250 offset:8448
	v_fma_f32 v250, -v123, v217, v202
	v_fma_f32 v209, v123, v216, v203
	v_fma_f32 v124, v122, v216, v250
	v_fma_f32 v132, v122, v217, v209
	v_cvt_pk_bf16_f32 v250, v124, v132
	ds_write_b32 v166, v250 offset:8448
	v_fma_f32 v250, -v123, v132, v204
	v_fma_f32 v209, v123, v124, v205
	v_fma_f32 v216, v122, v124, v250
	v_fma_f32 v217, v122, v132, v209
	v_cvt_pk_bf16_f32 v250, v216, v217
	ds_write_b32 v167, v250 offset:8448
	v_fma_f32 v250, -v123, v217, v210
	v_fma_f32 v209, v123, v216, v211
	v_fma_f32 v124, v122, v216, v250
	v_fma_f32 v132, v122, v217, v209
	v_cvt_pk_bf16_f32 v250, v124, v132
	ds_write_b32 v168, v250 offset:8448
	s_waitcnt lgkmcnt(0)
	ds_read_b128 v[82:85], v149 offset:8448
	ds_read_b128 v[86:89], v149 offset:8512
	ds_read_b128 v[170:173], v149 offset:8576
	ds_read_b128 v[178:181], v149 offset:8640
	s_waitcnt lgkmcnt(2)
	v_mfma_f32_16x16x32_bf16 v[86:89], v[42:45], v[86:89], 0
	v_mov_b32_e32 v125, v132
	v_mfma_f32_16x16x32_bf16 v[82:85], v[38:41], v[82:85], 0
	s_waitcnt lgkmcnt(0)
	v_mfma_f32_16x16x32_bf16 v[86:89], v[50:53], v[178:181], v[86:89]
	v_mfma_f32_16x16x32_bf16 v[82:85], v[46:49], v[170:173], v[82:85]
	s_nop 6
	v_add_f32_e64 v88, v88, 0
	v_add_f32_e64 v89, v89, 0
	v_pk_add_f32 v[86:87], v[86:87], 0 op_sel_hi:[1,0]
	v_pk_add_f32 v[84:85], v[84:85], v[88:89]
	v_pk_add_f32 v[82:83], v[82:83], v[86:87]
	s_waitcnt vmcnt(3)
	s_bitcmp1_b32 s23, 0
	s_cbranch_scc0 .Ls5_tail_codd
	v_pk_fma_f32 v[92:93], v[4:5], v[92:93], v[84:85]
	v_pk_fma_f32 v[90:91], v[2:3], v[90:91], v[82:83]
	v_mov_b64_e32 v[62:63], v[54:55]
	v_mov_b64_e32 v[64:65], v[56:57]
	v_mov_b64_e32 v[66:67], v[58:59]
	v_mov_b64_e32 v[68:69], v[60:61]
	v_cvt_pk_bf16_f32 v90, v90, v91
	v_cvt_pk_bf16_f32 v91, v92, v93
	v_lshl_add_u64 v[94:95], v[96:97], 1, v[128:129]
	global_store_dwordx2 v[94:95], v[90:91], off
	s_branch .Ls5_tail_done
.Ls5_tail_codd:
	v_pk_fma_f32 v[80:81], v[4:5], v[80:81], v[84:85]
	v_pk_fma_f32 v[78:79], v[2:3], v[78:79], v[82:83]
	v_mov_b64_e32 v[62:63], v[70:71]
	v_mov_b64_e32 v[64:65], v[72:73]
	v_mov_b64_e32 v[66:67], v[74:75]
	v_mov_b64_e32 v[68:69], v[76:77]
	v_cvt_pk_bf16_f32 v78, v78, v79
	v_cvt_pk_bf16_f32 v79, v80, v81
	v_lshl_add_u64 v[94:95], v[96:97], 1, v[128:129]
	global_store_dwordx2 v[94:95], v[78:79], off
.Ls5_tail_done:
	s_andn2_b64 exec, exec, s[54:55]
	s_cbranch_execz .LBB0_306


.LBB0_304:
	s_bitcmp1_b32 s23, 0
	s_cbranch_scc1 .Ls5_top_odd
	v_mov_b32_e32 v78, s22
	v_cndmask_b32_e32 v96, v169, v78, vcc
	v_ashrrev_i32_e32 v97, 31, v96
	s_add_i32 s0, s22, 16
	v_mov_b32_e32 v78, s0
	v_add_u32_e32 v79, -16, v169
	v_cndmask_b32_e32 v78, v79, v78, vcc
	v_ashrrev_i32_e32 v79, 31, v78
	v_lshlrev_b64 v[78:79], 12, v[78:79]
	v_lshl_add_u64 v[78:79], v[130:131], 0, v[78:79]
	global_load_dwordx4 v[78:81], v[78:79], off
	v_add_u32_e32 v70, v96, v0
	v_ashrrev_i32_e32 v71, 31, v70
	v_lshlrev_b64 v[70:71], 12, v[70:71]
	v_lshl_add_u64 v[74:75], v[126:127], 0, v[70:71]
	global_load_dwordx4 v[70:73], v[74:75], off offset:16
	s_nop 0
	global_load_dwordx4 v[74:77], v[74:75], off
	s_branch .LBB0_303
.Ls5_top_odd:
	v_mov_b32_e32 v90, s22
	v_cndmask_b32_e32 v96, v169, v90, vcc
	v_ashrrev_i32_e32 v97, 31, v96
	s_add_i32 s0, s22, 16
	v_mov_b32_e32 v90, s0
	v_add_u32_e32 v91, -16, v169
	v_cndmask_b32_e32 v90, v91, v90, vcc
	v_ashrrev_i32_e32 v91, 31, v90
	v_lshlrev_b64 v[90:91], 12, v[90:91]
	v_lshl_add_u64 v[90:91], v[130:131], 0, v[90:91]
	global_load_dwordx4 v[90:93], v[90:91], off
	v_add_u32_e32 v54, v96, v0
	v_ashrrev_i32_e32 v55, 31, v54
	v_lshlrev_b64 v[54:55], 12, v[54:55]
	v_lshl_add_u64 v[58:59], v[126:127], 0, v[54:55]
	global_load_dwordx4 v[54:57], v[58:59], off offset:16
	s_nop 0
	global_load_dwordx4 v[58:61], v[58:59], off
	s_branch .LBB0_303


.LBB0_306:
	s_waitcnt vmcnt(0)
	s_or_b64 exec, exec, s[54:55]
	s_and_saveexec_b64 s[0:1], s[2:3]
	s_cbranch_execz .LBB0_297
	v_lshlrev_b32_e32 v0, 2, v151
	v_or3_b32 v2, v0, s20, v150
	v_ashrrev_i32_e32 v3, 31, v2
	v_lshlrev_b64 v[2:3], 14, v[2:3]
	v_lshl_add_u64 v[2:3], s[26:27], 0, v[2:3]
	v_lshlrev_b32_e32 v0, 8, v121
	v_lshl_add_u64 v[2:3], v[2:3], 0, v[0:1]
	v_mov_b32_e32 v121, v1
	v_lshl_add_u64 v[2:3], v[2:3], 0, v[120:121]
	v_add_co_u32_e32 v4, vcc, 0xa800000, v2
	s_nop 1
	v_addc_co_u32_e32 v5, vcc, 0, v3, vcc
	v_add_co_u32_e32 v2, vcc, 0xaa00000, v2
	global_store_dword v[4:5], v124, off
	s_nop 0
	v_addc_co_u32_e32 v3, vcc, 0, v3, vcc
	global_store_dword v[2:3], v125, off
	s_branch .LBB0_297

.LBB0_703:
	s_cmp_lt_u32 s42, 4
	s_cselect_b64 s[22:23], -1, 0
	s_and_b64 s[22:23], s[4:5], s[22:23]
	s_andn2_b64 vcc, exec, s[22:23]
	s_mov_b64 s[62:63], -1
	s_cbranch_vccz .LBB0_706
	ds_read_b128 v[60:63], v146
	ds_read_b128 v[64:67], v146 offset:64
	s_waitcnt lgkmcnt(1)
	v_mfma_f32_16x16x32_bf16 v[60:63], v[60:63], v[4:7], 0
	s_waitcnt lgkmcnt(0)
	v_mfma_f32_16x16x32_bf16 v[96:99], v[64:67], v[8:11], v[60:63]
	ds_read_b128 v[64:67], v146 offset:2368
	s_nop 4
	ds_read_b128 v[60:63], v146 offset:2304
	s_waitcnt lgkmcnt(0)
	v_mfma_f32_16x16x32_bf16 v[60:63], v[60:63], v[4:7], 0
	v_max3_f32 v0, v96, s88, v97
	v_max3_f32 v0, v0, v98, v99
	v_mfma_f32_16x16x32_bf16 v[92:95], v[64:67], v[8:11], v[60:63]
	ds_read_b128 v[64:67], v146 offset:4672
	s_nop 3
	ds_read_b128 v[60:63], v146 offset:4608
	s_waitcnt lgkmcnt(0)
	v_mfma_f32_16x16x32_bf16 v[60:63], v[60:63], v[4:7], 0
	v_max3_f32 v0, v0, v92, v93
	v_max3_f32 v0, v0, v94, v95
	v_mfma_f32_16x16x32_bf16 v[88:91], v[64:67], v[8:11], v[60:63]
	ds_read_b128 v[64:67], v146 offset:6976
	s_nop 3
	ds_read_b128 v[60:63], v146 offset:6912
	s_waitcnt lgkmcnt(0)
	v_mfma_f32_16x16x32_bf16 v[60:63], v[60:63], v[4:7], 0
	v_max3_f32 v0, v0, v88, v89
	v_max3_f32 v0, v0, v90, v91
	v_mfma_f32_16x16x32_bf16 v[80:83], v[64:67], v[8:11], v[60:63]
	ds_read_b128 v[64:67], v146 offset:9280
	s_nop 3
	ds_read_b128 v[60:63], v146 offset:9216
	s_waitcnt lgkmcnt(0)
	v_mfma_f32_16x16x32_bf16 v[60:63], v[60:63], v[4:7], 0
	v_max3_f32 v0, v0, v80, v81
	v_max3_f32 v0, v0, v82, v83
	v_mfma_f32_16x16x32_bf16 v[76:79], v[64:67], v[8:11], v[60:63]
	ds_read_b128 v[64:67], v146 offset:11584
	s_nop 3
	ds_read_b128 v[60:63], v146 offset:11520
	s_waitcnt lgkmcnt(0)
	v_mfma_f32_16x16x32_bf16 v[60:63], v[60:63], v[4:7], 0
	v_max3_f32 v0, v0, v76, v77
	v_max3_f32 v0, v0, v78, v79
	v_mfma_f32_16x16x32_bf16 v[84:87], v[64:67], v[8:11], v[60:63]
	ds_read_b128 v[64:67], v146 offset:13888
	s_nop 3
	ds_read_b128 v[60:63], v146 offset:13824
	s_waitcnt lgkmcnt(0)
	v_mfma_f32_16x16x32_bf16 v[60:63], v[60:63], v[4:7], 0
	v_max3_f32 v0, v0, v84, v85
	v_max3_f32 v0, v0, v86, v87
	v_mfma_f32_16x16x32_bf16 v[100:103], v[64:67], v[8:11], v[60:63]
	ds_read_b128 v[64:67], v146 offset:16192
	s_nop 3
	ds_read_b128 v[60:63], v146 offset:16128
	s_waitcnt lgkmcnt(0)
	v_mfma_f32_16x16x32_bf16 v[60:63], v[60:63], v[4:7], 0
	v_max3_f32 v0, v0, v100, v101
	v_max3_f32 v0, v0, v102, v103
	v_mfma_f32_16x16x32_bf16 v[104:107], v[64:67], v[8:11], v[60:63]
	s_nop 7
	v_max3_f32 v0, v0, v104, v105
	v_max3_f32 v0, v0, v106, v107
	ds_bpermute_b32 v2, v142, v0
	s_waitcnt lgkmcnt(0)
	v_max_f32_e32 v2, v2, v2
	v_max_f32_e32 v0, v0, v2
	ds_bpermute_b32 v2, v143, v0
	s_waitcnt lgkmcnt(0)
	v_max3_f32 v0, v161, v0, v2
	v_sub_f32_e32 v2, v161, v0
	v_exp_f32_e32 v2, v2
	s_nop 0
	v_pk_mul_f32 v[74:75], v[58:59], v[2:3] op_sel_hi:[1,0]
	v_pk_mul_f32 v[72:73], v[56:57], v[2:3] op_sel_hi:[1,0]
	v_pk_mul_f32 v[70:71], v[54:55], v[2:3] op_sel_hi:[1,0]
	v_pk_mul_f32 v[68:69], v[52:53], v[2:3] op_sel_hi:[1,0]
	v_pk_mul_f32 v[66:67], v[50:51], v[2:3] op_sel_hi:[1,0]
	v_pk_mul_f32 v[64:65], v[48:49], v[2:3] op_sel_hi:[1,0]
	v_pk_mul_f32 v[62:63], v[46:47], v[2:3] op_sel_hi:[1,0]
	v_pk_mul_f32 v[60:61], v[44:45], v[2:3] op_sel_hi:[1,0]
	v_sub_f32_e32 v3, v96, v0
	v_exp_f32_e32 v96, v3
	v_sub_f32_e32 v3, v97, v0
	v_exp_f32_e32 v97, v3
	v_sub_f32_e32 v3, v98, v0
	v_exp_f32_e32 v98, v3
	v_sub_f32_e32 v3, v99, v0
	v_exp_f32_e32 v99, v3
	v_sub_f32_e32 v3, v92, v0
	v_exp_f32_e32 v92, v3
	v_sub_f32_e32 v3, v93, v0
	v_exp_f32_e32 v93, v3
	v_sub_f32_e32 v3, v94, v0
	v_exp_f32_e32 v94, v3
	v_sub_f32_e32 v3, v95, v0
	v_exp_f32_e32 v95, v3
	v_sub_f32_e32 v3, v88, v0
	v_exp_f32_e32 v119, v3
	v_sub_f32_e32 v3, v89, v0
	v_exp_f32_e32 v162, v3
	v_sub_f32_e32 v3, v90, v0
	v_exp_f32_e32 v163, v3
	v_sub_f32_e32 v3, v91, v0
	v_exp_f32_e32 v164, v3
	v_sub_f32_e32 v3, v80, v0
	v_exp_f32_e32 v165, v3
	v_sub_f32_e32 v3, v81, v0
	v_exp_f32_e32 v166, v3
	v_sub_f32_e32 v3, v82, v0
	v_exp_f32_e32 v167, v3
	v_sub_f32_e32 v3, v83, v0
	v_exp_f32_e32 v83, v3
	v_sub_f32_e32 v3, v76, v0
	v_fma_f32 v2, v160, v2, v96
	v_exp_f32_e32 v168, v3
	v_sub_f32_e32 v3, v77, v0
	v_add_f32_e32 v2, v97, v2
	v_exp_f32_e32 v169, v3
	v_sub_f32_e32 v3, v78, v0
	v_add_f32_e32 v2, v98, v2
	v_exp_f32_e32 v170, v3
	v_sub_f32_e32 v3, v79, v0
	v_add_f32_e32 v2, v99, v2
	v_exp_f32_e32 v171, v3
	v_sub_f32_e32 v3, v84, v0
	v_add_f32_e32 v2, v92, v2
	v_exp_f32_e32 v172, v3
	v_sub_f32_e32 v3, v85, v0
	v_add_f32_e32 v2, v93, v2
	v_exp_f32_e32 v173, v3
	v_sub_f32_e32 v3, v86, v0
	v_cvt_pk_bf16_f32 v86, v92, v93
	ds_read_b64_tr_b16 v[90:91], v140 offset:20736
	ds_read_b64_tr_b16 v[88:89], v140 offset:18432
	ds_read_b64_tr_b16 v[92:93], v140 offset:18464
	v_add_f32_e32 v2, v94, v2
	v_exp_f32_e32 v178, v3
	v_sub_f32_e32 v3, v87, v0
	v_cvt_pk_bf16_f32 v84, v96, v97
	v_cvt_pk_bf16_f32 v85, v98, v99
	v_cvt_pk_bf16_f32 v87, v94, v95
	v_add_f32_e32 v2, v95, v2
	ds_read_b64_tr_b16 v[94:95], v140 offset:20768
	s_waitcnt lgkmcnt(2)
	v_mfma_f32_16x16x32_bf16 v[72:75], v[88:91], v[84:87], v[72:75]
	ds_read_b64_tr_b16 v[88:89], v140 offset:18496
	ds_read_b64_tr_b16 v[90:91], v140 offset:20800
	v_exp_f32_e32 v179, v3
	v_add_f32_e32 v2, v119, v2
	s_waitcnt lgkmcnt(0)
	v_mfma_f32_16x16x32_bf16 v[64:67], v[88:91], v[84:87], v[64:67]
	ds_read_b64_tr_b16 v[88:89], v140 offset:18528
	ds_read_b64_tr_b16 v[90:91], v140 offset:20832
	v_add_f32_e32 v2, v162, v2
	v_add_f32_e32 v2, v163, v2
	s_waitcnt lgkmcnt(0)
	v_mfma_f32_16x16x32_bf16 v[60:63], v[88:91], v[84:87], v[60:63]
	ds_read_b64_tr_b16 v[88:89], v140 offset:23040
	ds_read_b64_tr_b16 v[90:91], v140 offset:25344
	v_add_f32_e32 v2, v164, v2
	v_add_f32_e32 v2, v165, v2
	v_mfma_f32_16x16x32_bf16 v[68:71], v[92:95], v[84:87], v[68:71]
	v_cvt_pk_bf16_f32 v84, v119, v162
	v_cvt_pk_bf16_f32 v85, v163, v164
	v_cvt_pk_bf16_f32 v86, v165, v166
	v_cvt_pk_bf16_f32 v87, v167, v83
	v_add_f32_e32 v2, v166, v2
	v_add_f32_e32 v2, v167, v2
	s_waitcnt lgkmcnt(0)
	v_mfma_f32_16x16x32_bf16 v[72:75], v[88:91], v[84:87], v[72:75]
	ds_read_b64_tr_b16 v[88:89], v140 offset:23072
	ds_read_b64_tr_b16 v[90:91], v140 offset:25376
	v_add_f32_e32 v2, v83, v2
	v_add_f32_e32 v2, v168, v2
	s_waitcnt lgkmcnt(0)
	v_mfma_f32_16x16x32_bf16 v[68:71], v[88:91], v[84:87], v[68:71]
	ds_read_b64_tr_b16 v[88:89], v140 offset:23104
	ds_read_b64_tr_b16 v[90:91], v140 offset:25408
	v_add_f32_e32 v2, v169, v2
	v_add_f32_e32 v2, v170, v2
	s_waitcnt lgkmcnt(0)
	v_mfma_f32_16x16x32_bf16 v[64:67], v[88:91], v[84:87], v[64:67]
	ds_read_b64_tr_b16 v[88:89], v140 offset:23136
	ds_read_b64_tr_b16 v[90:91], v140 offset:25440
	v_add_f32_e32 v2, v171, v2
	v_sub_f32_e32 v3, v100, v0
	s_waitcnt lgkmcnt(0)
	v_mfma_f32_16x16x32_bf16 v[60:63], v[88:91], v[84:87], v[60:63]
	ds_read_b64_tr_b16 v[88:89], v140 offset:27648
	ds_read_b64_tr_b16 v[90:91], v140 offset:29952
	v_cvt_pk_bf16_f32 v84, v168, v169
	v_cvt_pk_bf16_f32 v85, v170, v171
	v_cvt_pk_bf16_f32 v86, v172, v173
	v_cvt_pk_bf16_f32 v87, v178, v179
	v_add_f32_e32 v2, v172, v2
	v_exp_f32_e32 v3, v3
	s_waitcnt lgkmcnt(0)
	v_mfma_f32_16x16x32_bf16 v[72:75], v[88:91], v[84:87], v[72:75]
	ds_read_b64_tr_b16 v[88:89], v140 offset:27680
	ds_read_b64_tr_b16 v[90:91], v140 offset:29984
	v_sub_f32_e32 v76, v101, v0
	v_add_f32_e32 v2, v173, v2
	s_waitcnt lgkmcnt(0)
	v_mfma_f32_16x16x32_bf16 v[68:71], v[88:91], v[84:87], v[68:71]
	ds_read_b64_tr_b16 v[88:89], v140 offset:27712
	ds_read_b64_tr_b16 v[90:91], v140 offset:30016
	v_exp_f32_e32 v76, v76
	v_sub_f32_e32 v77, v102, v0
	s_waitcnt lgkmcnt(0)
	v_mfma_f32_16x16x32_bf16 v[88:91], v[88:91], v[84:87], v[64:67]
	s_nop 2
	ds_read_b64_tr_b16 v[64:65], v140 offset:27744
	ds_read_b64_tr_b16 v[66:67], v140 offset:30048
	v_add_f32_e32 v2, v178, v2
	v_exp_f32_e32 v77, v77
	v_sub_f32_e32 v78, v103, v0
	v_add_f32_e32 v2, v179, v2
	v_exp_f32_e32 v78, v78
	v_sub_f32_e32 v79, v104, v0
	v_sub_f32_e32 v80, v105, v0
	v_sub_f32_e32 v81, v106, v0
	v_sub_f32_e32 v82, v107, v0
	v_add_f32_e32 v2, v3, v2
	v_exp_f32_e32 v79, v79
	v_exp_f32_e32 v80, v80
	v_exp_f32_e32 v81, v81
	v_exp_f32_e32 v82, v82
	s_waitcnt lgkmcnt(0)
	v_mfma_f32_16x16x32_bf16 v[84:87], v[64:67], v[84:87], v[60:63]
	s_nop 2
	ds_read_b64_tr_b16 v[60:61], v140 offset:32256
	ds_read_b64_tr_b16 v[62:63], v140 offset:34560
	ds_read_b64_tr_b16 v[64:65], v140 offset:32288
	ds_read_b64_tr_b16 v[66:67], v140 offset:34592
	v_add_f32_e32 v2, v76, v2
	v_add_f32_e32 v2, v77, v2
	v_add_f32_e32 v2, v78, v2
	v_add_f32_e32 v2, v79, v2
	v_cvt_pk_bf16_f32 v76, v3, v76
	v_cvt_pk_bf16_f32 v77, v77, v78
	v_cvt_pk_bf16_f32 v78, v79, v80
	v_cvt_pk_bf16_f32 v79, v81, v82
	v_add_f32_e32 v2, v80, v2
	v_add_f32_e32 v2, v81, v2
	s_waitcnt lgkmcnt(2)
	v_mfma_f32_16x16x32_bf16 v[60:63], v[60:63], v[76:79], v[72:75]
	v_add_f32_e32 v2, v82, v2
	s_waitcnt lgkmcnt(0)
	v_mfma_f32_16x16x32_bf16 v[64:67], v[64:67], v[76:79], v[68:71]
	s_nop 2
	ds_read_b64_tr_b16 v[68:69], v140 offset:32320
	ds_read_b64_tr_b16 v[70:71], v140 offset:34624
	ds_read_b64_tr_b16 v[72:73], v140 offset:32352
	ds_read_b64_tr_b16 v[74:75], v140 offset:34656
	s_waitcnt lgkmcnt(2)
	v_mfma_f32_16x16x32_bf16 v[68:71], v[68:71], v[76:79], v[88:91]
	s_waitcnt lgkmcnt(0)
	v_mfma_f32_16x16x32_bf16 v[72:75], v[72:75], v[76:79], v[84:87]
	s_cbranch_execz .LBB0_707

.LBB0_707:
	ds_read_b128 v[60:63], v159
	ds_read_b128 v[64:67], v159 offset:64
	v_lshl_add_u32 v0, s42, 1, v117
	s_nop 1
	v_mul_lo_u32 v70, v0, 31
	v_lshl_add_u32 v0, v70, 2, v147
	s_waitcnt lgkmcnt(1)
	v_mfma_f32_16x16x32_bf16 v[60:63], v[60:63], v[4:7], 0
	v_mov_b32_e32 v69, 0xf149f2ca
	s_waitcnt lgkmcnt(0)
	v_mfma_f32_16x16x32_bf16 v[60:63], v[64:67], v[8:11], v[60:63]
	v_mov_b32_e32 v66, 0xf149f2ca
	s_and_saveexec_b64 s[62:63], s[6:7]
	s_cbranch_execz .LBB0_709
	ds_read_b32 v2, v0 offset:37792
	s_waitcnt lgkmcnt(0)
	s_nop 2
	v_add_f32_e32 v69, v60, v2
